# P6 epilogue de-serialisation: the 8 row-scale loads are issued together with the 4 column-scale loads (one load-latency wait per unit instead of two)
# baseline (speedup 1.0000x reference)
.LBB0_1241:
	s_bfe_u32 s38, s66, 0x80008
	s_lshl_b32 s8, s38, 8
	v_mov_b32_e32 v16, v176
	v_mov_b32_e32 v42, v175
	s_or_b32 s8, s8, s50
	s_and_b32 s37, s66, 0xf0000
	v_lshl_add_u32 v156, v16, 3, s8
	v_ashrrev_i32_e32 v157, 31, v156
	v_lshl_add_u64 v[40:41], v[156:157], 2, s[16:17]
	global_load_dwordx4 v[16:19], v[40:41], off
	global_load_dwordx4 v[24:27], v[40:41], off offset:16
	global_load_dwordx4 v[162:165], v[40:41], off offset:512
	global_load_dwordx4 v[166:169], v[40:41], off offset:528
	s_lshl_b32 s8, s66, 8
	s_and_b32 s36, s8, 0xff00
	v_add_u32_e32 v172, s49, v42
	v_add_u32_e32 v160, s36, v172
	s_cmp_eq_u32 s37, 0
	v_ashrrev_i32_e32 v161, 31, v160
	v_lshl_add_u64 v[208:209], v[160:161], 2, s[14:15]
	global_load_dword v200, v[208:209], off
	global_load_dword v201, v[208:209], off offset:64
	global_load_dword v202, v[208:209], off offset:128
	global_load_dword v203, v[208:209], off offset:192
	global_load_dword v204, v[208:209], off offset:512
	global_load_dword v205, v[208:209], off offset:576
	global_load_dword v206, v[208:209], off offset:640
	global_load_dword v207, v[208:209], off offset:704
	s_waitcnt vmcnt(0)
	v_pk_mul_f32 v[88:89], v[16:17], s[26:27] op_sel_hi:[1,0]
	v_pk_mul_f32 v[40:41], v[24:25], s[26:27] op_sel_hi:[1,0]
	v_pk_mul_f32 v[24:25], v[162:163], s[26:27] op_sel_hi:[1,0]
	v_pk_mul_f32 v[16:17], v[166:167], s[26:27] op_sel_hi:[1,0]
	v_pk_mul_f32 v[90:91], v[18:19], s[26:27] op_sel_hi:[1,0]
	v_pk_mul_f32 v[42:43], v[26:27], s[26:27] op_sel_hi:[1,0]
	v_pk_mul_f32 v[26:27], v[164:165], s[26:27] op_sel_hi:[1,0]
	v_pk_mul_f32 v[18:19], v[168:169], s[26:27] op_sel_hi:[1,0]
	v_pk_mul_f32 v[170:171], v[88:89], v[140:141]
	v_pk_mul_f32 v[168:169], v[40:41], v[142:143]
	v_pk_mul_f32 v[166:167], v[24:25], v[144:145]
	v_pk_mul_f32 v[164:165], v[16:17], v[146:147]
	v_pk_mul_f32 v[162:163], v[88:89], v[116:117]
	v_pk_mul_f32 v[150:151], v[40:41], v[112:113]
	v_pk_mul_f32 v[146:147], v[24:25], v[114:115]
	v_pk_mul_f32 v[144:145], v[16:17], v[118:119]
	v_pk_mul_f32 v[142:143], v[88:89], v[104:105]
	v_pk_mul_f32 v[140:141], v[40:41], v[96:97]
	v_pk_mul_f32 v[118:119], v[24:25], v[148:149]
	v_pk_mul_f32 v[116:117], v[16:17], v[152:153]
	v_pk_mul_f32 v[114:115], v[88:89], v[98:99]
	v_pk_mul_f32 v[112:113], v[40:41], v[106:107]
	v_pk_mul_f32 v[106:107], v[24:25], v[154:155]
	v_pk_mul_f32 v[98:99], v[16:17], v[158:159]
	s_cbranch_scc1 .LBB0_1248
	v_lshl_add_u64 v[96:97], v[160:161], 2, s[14:15]
	global_load_dword v148, v[96:97], off
	s_lshr_b32 s8, s66, 13
	v_ashrrev_i32_e32 v173, 31, v172
	s_and_b32 s8, s8, 0x7f80
	v_mov_b64_e32 v[96:97], s[82:83]
	v_add_u32_e32 v192, 16, v172
	v_lshl_add_u64 v[180:181], v[172:173], 0, s[8:9]
	v_add_u32_e32 v154, s36, v192
	v_mad_u64_u32 v[182:183], s[40:41], v180, s61, v[96:97]
	v_lshlrev_b64 v[104:105], 2, v[156:157]
	v_pk_mul_f32 v[152:153], v[90:91], v[124:125]
	v_ashrrev_i32_e32 v155, 31, v154
	v_mad_i32_i24 v183, v181, s61, v183
	v_pk_mul_f32 v[158:159], v[42:43], v[120:121]
	v_pk_mul_f32 v[184:185], v[26:27], v[122:123]
	v_pk_mul_f32 v[188:189], v[18:19], v[126:127]
	v_lshl_add_u64 v[194:195], v[154:155], 2, s[14:15]
	v_lshl_add_u64 v[196:197], v[182:183], 0, v[104:105]
	v_ashrrev_i32_e32 v193, 31, v192
	s_waitcnt vmcnt(0)
	v_pk_mul_f32 v[154:155], v[152:153], v[148:149] op_sel_hi:[1,0]
	v_pk_mul_f32 v[152:153], v[170:171], v[148:149] op_sel_hi:[1,0]
	v_pk_mul_f32 v[182:183], v[158:159], v[148:149] op_sel_hi:[1,0]
	v_pk_mul_f32 v[180:181], v[168:169], v[148:149] op_sel_hi:[1,0]
	v_pk_mul_f32 v[186:187], v[184:185], v[148:149] op_sel_hi:[1,0]
	v_pk_mul_f32 v[184:185], v[166:167], v[148:149] op_sel_hi:[1,0]
	v_pk_mul_f32 v[190:191], v[188:189], v[148:149] op_sel_hi:[1,0]
	v_pk_mul_f32 v[188:189], v[164:165], v[148:149] op_sel_hi:[1,0]
	global_store_dwordx4 v[196:197], v[152:155], off
	global_store_dwordx4 v[196:197], v[180:183], off offset:16
	global_store_dwordx4 v[196:197], v[184:187], off offset:512
	global_store_dwordx4 v[196:197], v[188:191], off offset:528
	global_load_dword v148, v[194:195], off
	v_add_u32_e32 v194, 32, v172
	v_lshl_add_u64 v[180:181], v[192:193], 0, s[8:9]
	v_add_u32_e32 v154, s36, v194
	v_mad_u64_u32 v[182:183], s[40:41], v180, s61, v[96:97]
	v_pk_mul_f32 v[152:153], v[90:91], v[108:109]
	v_ashrrev_i32_e32 v155, 31, v154
	v_mad_i32_i24 v183, v181, s61, v183
	v_pk_mul_f32 v[158:159], v[42:43], v[110:111]
	v_pk_mul_f32 v[184:185], v[26:27], v[100:101]
	v_pk_mul_f32 v[188:189], v[18:19], v[102:103]
	v_lshl_add_u64 v[192:193], v[154:155], 2, s[14:15]
	v_lshl_add_u64 v[196:197], v[182:183], 0, v[104:105]
	v_ashrrev_i32_e32 v195, 31, v194
	v_add_u32_e32 v172, 48, v172
	v_ashrrev_i32_e32 v173, 31, v172
	s_waitcnt vmcnt(0)
	v_pk_mul_f32 v[154:155], v[152:153], v[148:149] op_sel_hi:[1,0]
	v_pk_mul_f32 v[152:153], v[162:163], v[148:149] op_sel_hi:[1,0]
	v_pk_mul_f32 v[182:183], v[158:159], v[148:149] op_sel_hi:[1,0]
	v_pk_mul_f32 v[180:181], v[150:151], v[148:149] op_sel_hi:[1,0]
	v_pk_mul_f32 v[186:187], v[184:185], v[148:149] op_sel_hi:[1,0]
	v_pk_mul_f32 v[184:185], v[146:147], v[148:149] op_sel_hi:[1,0]
	v_pk_mul_f32 v[190:191], v[188:189], v[148:149] op_sel_hi:[1,0]
	v_pk_mul_f32 v[188:189], v[144:145], v[148:149] op_sel_hi:[1,0]
	global_store_dwordx4 v[196:197], v[152:155], off
	global_store_dwordx4 v[196:197], v[180:183], off offset:16
	global_store_dwordx4 v[196:197], v[184:187], off offset:512
	global_store_dwordx4 v[196:197], v[188:191], off offset:528
	global_load_dword v148, v[192:193], off
	v_lshl_add_u64 v[180:181], v[194:195], 0, s[8:9]
	v_add_u32_e32 v154, s36, v172
	v_mad_u64_u32 v[182:183], s[36:37], v180, s61, v[96:97]
	v_pk_mul_f32 v[152:153], v[90:91], v[84:85]
	v_ashrrev_i32_e32 v155, 31, v154
	v_mad_i32_i24 v183, v181, s61, v183
	v_pk_mul_f32 v[158:159], v[42:43], v[86:87]
	v_pk_mul_f32 v[184:185], v[26:27], v[92:93]
	v_pk_mul_f32 v[188:189], v[18:19], v[94:95]
	v_lshl_add_u64 v[192:193], v[154:155], 2, s[14:15]
	v_lshl_add_u64 v[194:195], v[182:183], 0, v[104:105]
	s_waitcnt vmcnt(0)
	v_pk_mul_f32 v[154:155], v[152:153], v[148:149] op_sel_hi:[1,0]
	v_pk_mul_f32 v[152:153], v[142:143], v[148:149] op_sel_hi:[1,0]
	v_pk_mul_f32 v[182:183], v[158:159], v[148:149] op_sel_hi:[1,0]
	v_pk_mul_f32 v[180:181], v[140:141], v[148:149] op_sel_hi:[1,0]
	v_pk_mul_f32 v[186:187], v[184:185], v[148:149] op_sel_hi:[1,0]
	v_pk_mul_f32 v[184:185], v[118:119], v[148:149] op_sel_hi:[1,0]
	v_pk_mul_f32 v[190:191], v[188:189], v[148:149] op_sel_hi:[1,0]
	v_pk_mul_f32 v[188:189], v[116:117], v[148:149] op_sel_hi:[1,0]
	global_store_dwordx4 v[194:195], v[152:155], off
	global_store_dwordx4 v[194:195], v[180:183], off offset:16
	global_store_dwordx4 v[194:195], v[184:187], off offset:512
	global_store_dwordx4 v[194:195], v[188:191], off offset:528
	global_load_dword v148, v[192:193], off
	v_lshl_add_u64 v[154:155], v[172:173], 0, s[8:9]
	v_mad_u64_u32 v[96:97], s[36:37], v154, s61, v[96:97]
	v_pk_mul_f32 v[152:153], v[90:91], v[76:77]
	v_mad_i32_i24 v97, v155, s61, v97
	v_pk_mul_f32 v[158:159], v[42:43], v[78:79]
	v_pk_mul_f32 v[184:185], v[26:27], v[80:81]
	v_pk_mul_f32 v[188:189], v[18:19], v[82:83]
	v_lshl_add_u64 v[96:97], v[96:97], 0, v[104:105]
	s_waitcnt vmcnt(0)
	v_pk_mul_f32 v[154:155], v[152:153], v[148:149] op_sel_hi:[1,0]
	v_pk_mul_f32 v[152:153], v[114:115], v[148:149] op_sel_hi:[1,0]
	v_pk_mul_f32 v[182:183], v[158:159], v[148:149] op_sel_hi:[1,0]
	v_pk_mul_f32 v[180:181], v[112:113], v[148:149] op_sel_hi:[1,0]
	v_pk_mul_f32 v[186:187], v[184:185], v[148:149] op_sel_hi:[1,0]
	v_pk_mul_f32 v[184:185], v[106:107], v[148:149] op_sel_hi:[1,0]
	v_pk_mul_f32 v[190:191], v[188:189], v[148:149] op_sel_hi:[1,0]
	v_pk_mul_f32 v[188:189], v[98:99], v[148:149] op_sel_hi:[1,0]
	global_store_dwordx4 v[96:97], v[152:155], off
	global_store_dwordx4 v[96:97], v[180:183], off offset:16
	global_store_dwordx4 v[96:97], v[184:187], off offset:512
	global_store_dwordx4 v[96:97], v[188:191], off offset:528
	s_cbranch_execnz .LBB0_1244
.LBB0_1243:
	v_lshl_add_u64 v[152:153], v[160:161], 2, s[14:15]
	v_mov_b32_e32 v154, v200
	v_mov_b32_e32 v158, v201
	s_lshl_b32 s8, s38, 7
	v_pk_mul_f32 v[172:173], v[90:91], v[124:125]
	v_pk_mul_f32 v[180:181], v[42:43], v[120:121]
	v_pk_mul_f32 v[182:183], v[26:27], v[122:123]
	v_pk_mul_f32 v[184:185], v[90:91], v[108:109]
	v_pk_mul_f32 v[186:187], v[42:43], v[110:111]
	v_subrev_u32_e32 v108, s8, v156
	v_mov_b32_e32 v156, v202
	v_mov_b32_e32 v124, v203
	v_mov_b32_e32 v122, v204
	v_mov_b32_e32 v120, v205
	v_mov_b32_e32 v110, v206
	v_mov_b32_e32 v104, v207
	v_add_u32_e32 v155, 16, v160
	v_mov_b64_e32 v[96:97], s[18:19]
	v_ashrrev_i32_e32 v109, 31, v108
	v_mad_i64_i32 v[152:153], s[36:37], v160, s62, v[96:97]
	v_lshlrev_b64 v[108:109], 1, v[108:109]
	v_lshl_add_u64 v[188:189], v[152:153], 0, v[108:109]
	v_add_u32_e32 v159, 48, v160
	v_pk_mul_f32 v[126:127], v[18:19], v[126:127]
	v_add_u32_e32 v157, 32, v160
	v_add_u32_e32 v179, 0x80, v160
	v_add_u32_e32 v149, 0x90, v160
	v_add_u32_e32 v148, 0xa0, v160
	v_add_u32_e32 v105, 0xb0, v160
	v_mad_i64_i32 v[160:161], s[36:37], v155, s62, v[96:97]
	v_pk_mul_f32 v[100:101], v[26:27], v[100:101]
	v_pk_mul_f32 v[102:103], v[18:19], v[102:103]
	v_lshl_add_u64 v[160:161], v[160:161], 0, v[108:109]
	v_pk_mul_f32 v[84:85], v[90:91], v[84:85]
	v_pk_mul_f32 v[92:93], v[26:27], v[92:93]
	v_pk_mul_f32 v[86:87], v[42:43], v[86:87]
	v_pk_mul_f32 v[94:95], v[18:19], v[94:95]
	v_pk_mul_f32 v[76:77], v[90:91], v[76:77]
	v_pk_mul_f32 v[80:81], v[26:27], v[80:81]
	v_pk_mul_f32 v[78:79], v[42:43], v[78:79]
	v_pk_mul_f32 v[82:83], v[18:19], v[82:83]
	v_pk_mul_f32 v[64:65], v[88:89], v[64:65]
	v_pk_mul_f32 v[66:67], v[90:91], v[66:67]
	v_pk_mul_f32 v[70:71], v[24:25], v[70:71]
	v_pk_mul_f32 v[60:61], v[40:41], v[60:61]
	v_pk_mul_f32 v[62:63], v[42:43], v[62:63]
	v_pk_mul_f32 v[68:69], v[16:17], v[68:69]
	v_pk_mul_f32 v[72:73], v[18:19], v[72:73]
	v_pk_mul_f32 v[74:75], v[26:27], v[74:75]
	v_pk_mul_f32 v[46:47], v[88:89], v[46:47]
	v_pk_mul_f32 v[52:53], v[90:91], v[52:53]
	v_pk_mul_f32 v[54:55], v[24:25], v[54:55]
	v_pk_mul_f32 v[44:45], v[40:41], v[44:45]
	v_pk_mul_f32 v[48:49], v[42:43], v[48:49]
	v_pk_mul_f32 v[50:51], v[16:17], v[50:51]
	v_pk_mul_f32 v[56:57], v[18:19], v[56:57]
	v_pk_mul_f32 v[58:59], v[26:27], v[58:59]
	v_pk_mul_f32 v[22:23], v[88:89], v[22:23]
	v_pk_mul_f32 v[10:11], v[88:89], v[10:11]
	v_pk_mul_f32 v[32:33], v[16:17], v[32:33]
	v_pk_mul_f32 v[0:1], v[16:17], v[0:1]
	v_pk_mul_f32 v[30:31], v[90:91], v[30:31]
	v_pk_mul_f32 v[34:35], v[24:25], v[34:35]
	v_pk_mul_f32 v[14:15], v[90:91], v[14:15]
	v_pk_mul_f32 v[4:5], v[24:25], v[4:5]
	v_pk_mul_f32 v[20:21], v[40:41], v[20:21]
	v_pk_mul_f32 v[8:9], v[40:41], v[8:9]
	v_pk_mul_f32 v[6:7], v[26:27], v[6:7]
	v_pk_mul_f32 v[28:29], v[42:43], v[28:29]
	v_pk_mul_f32 v[12:13], v[42:43], v[12:13]
	v_pk_mul_f32 v[36:37], v[18:19], v[36:37]
	v_pk_mul_f32 v[38:39], v[26:27], v[38:39]
	v_pk_mul_f32 v[2:3], v[18:19], v[2:3]
	s_waitcnt vmcnt(0)
	v_pk_mul_f32 v[170:171], v[170:171], v[154:155] op_sel_hi:[1,0]
	v_pk_mul_f32 v[152:153], v[172:173], v[154:155] op_sel_hi:[1,0]
	v_pk_mul_f32 v[168:169], v[168:169], v[154:155] op_sel_hi:[1,0]
	v_mul_f32_e32 v111, 0xbfb8aa3b, v170
	v_pk_mul_f32 v[172:173], v[180:181], v[154:155] op_sel_hi:[1,0]
	v_pk_mul_f32 v[180:181], v[182:183], v[154:155] op_sel_hi:[1,0]
	v_mul_f32_e32 v121, 0xbfb8aa3b, v171
	v_mul_f32_e32 v123, 0xbfb8aa3b, v152
	v_mul_f32_e32 v182, 0xbfb8aa3b, v168
	v_exp_f32_e32 v111, v111
	v_exp_f32_e32 v121, v121
	v_exp_f32_e32 v123, v123
	v_exp_f32_e32 v182, v182
	v_add_f32_e32 v111, 1.0, v111
	v_mul_f32_e32 v125, 0xbfb8aa3b, v153
	v_mul_f32_e32 v183, 0xbfb8aa3b, v169
	v_add_f32_e32 v121, 1.0, v121
	v_add_f32_e32 v123, 1.0, v123
	v_add_f32_e32 v182, 1.0, v182
	v_rcp_f32_e32 v111, v111
	v_exp_f32_e32 v125, v125
	v_exp_f32_e32 v183, v183
	v_rcp_f32_e32 v121, v121
	v_rcp_f32_e32 v123, v123
	v_rcp_f32_e32 v182, v182
	v_pk_mul_f32 v[166:167], v[166:167], v[154:155] op_sel_hi:[1,0]
	v_mul_f32_e32 v111, v170, v111
	v_pk_mul_f32 v[126:127], v[126:127], v[154:155] op_sel_hi:[1,0]
	v_pk_mul_f32 v[154:155], v[164:165], v[154:155] op_sel_hi:[1,0]
	v_pk_mul_f32 v[162:163], v[162:163], v[158:159] op_sel_hi:[1,0]
	v_add_f32_e32 v125, 1.0, v125
	v_add_f32_e32 v183, 1.0, v183
	v_mul_f32_e32 v121, v171, v121
	v_mul_f32_e32 v123, v152, v123
	v_mul_f32_e32 v152, v168, v182
	v_mul_f32_e32 v111, v166, v111
	v_rcp_f32_e32 v125, v125
	v_rcp_f32_e32 v183, v183
	v_mul_f32_e32 v121, v167, v121
	v_mul_f32_e32 v154, v154, v152
	v_cvt_pk_bf16_f32 v152, v111, v121
	v_mul_f32_e32 v111, 0xbfb8aa3b, v162
	v_exp_f32_e32 v111, v111
	v_pk_mul_f32 v[164:165], v[184:185], v[158:159] op_sel_hi:[1,0]
	v_mul_f32_e32 v125, v153, v125
	v_mul_f32_e32 v153, v169, v183
	v_mul_f32_e32 v123, v180, v123
	v_mul_f32_e32 v125, v181, v125
	v_mul_f32_e32 v155, v155, v153
	v_cvt_pk_bf16_f32 v153, v123, v125
	v_add_f32_e32 v111, 1.0, v111
	v_mul_f32_e32 v123, 0xbfb8aa3b, v164
	v_rcp_f32_e32 v111, v111
	v_exp_f32_e32 v123, v123
	v_mul_f32_e32 v125, 0xbfb8aa3b, v165
	v_exp_f32_e32 v125, v125
	v_mul_f32_e32 v184, 0xbfb8aa3b, v172
	v_mul_f32_e32 v185, 0xbfb8aa3b, v173
	v_exp_f32_e32 v184, v184
	v_exp_f32_e32 v185, v185
	v_pk_mul_f32 v[150:151], v[150:151], v[158:159] op_sel_hi:[1,0]
	v_pk_mul_f32 v[146:147], v[146:147], v[158:159] op_sel_hi:[1,0]
	v_mul_f32_e32 v111, v162, v111
	v_add_f32_e32 v123, 1.0, v123
	v_mul_f32_e32 v111, v146, v111
	v_rcp_f32_e32 v123, v123
	v_add_f32_e32 v125, 1.0, v125
	v_mul_f32_e32 v146, 0xbfb8aa3b, v150
	v_rcp_f32_e32 v125, v125
	v_exp_f32_e32 v146, v146
	v_add_f32_e32 v184, 1.0, v184
	v_add_f32_e32 v185, 1.0, v185
	v_rcp_f32_e32 v184, v184
	v_rcp_f32_e32 v185, v185
	v_pk_mul_f32 v[100:101], v[100:101], v[158:159] op_sel_hi:[1,0]
	v_mul_f32_e32 v123, v164, v123
	v_mul_f32_e32 v123, v100, v123
	v_mul_f32_e32 v100, v165, v125
	v_add_f32_e32 v125, 1.0, v146
	v_rcp_f32_e32 v125, v125
	v_mul_f32_e32 v146, 0xbfb8aa3b, v151
	v_mul_f32_e32 v168, v172, v184
	v_mul_f32_e32 v169, v173, v185
	v_exp_f32_e32 v146, v146
	v_mul_f32_e32 v126, v126, v168
	v_mul_f32_e32 v127, v127, v169
	v_cvt_pk_bf16_f32 v154, v154, v155
	v_cvt_pk_bf16_f32 v155, v126, v127
	v_pk_mul_f32 v[126:127], v[186:187], v[158:159] op_sel_hi:[1,0]
	v_pk_mul_f32 v[144:145], v[144:145], v[158:159] op_sel_hi:[1,0]
	v_mul_f32_e32 v101, v101, v100
	v_mul_f32_e32 v100, v150, v125
	v_mul_f32_e32 v125, v144, v100
	v_mul_f32_e32 v144, 0xbfb8aa3b, v126
	v_add_f32_e32 v100, 1.0, v146
	v_exp_f32_e32 v144, v144
	v_mul_f32_e32 v146, 0xbfb8aa3b, v127
	v_mul_f32_e32 v121, 0xbfb8aa3b, v163
	v_exp_f32_e32 v146, v146
	v_exp_f32_e32 v121, v121
	v_rcp_f32_e32 v100, v100
	v_add_f32_e32 v144, 1.0, v144
	v_rcp_f32_e32 v144, v144
	v_add_f32_e32 v146, 1.0, v146
	v_add_f32_e32 v121, 1.0, v121
	v_rcp_f32_e32 v146, v146
	v_rcp_f32_e32 v121, v121
	v_mul_f32_e32 v100, v151, v100
	v_pk_mul_f32 v[102:103], v[102:103], v[158:159] op_sel_hi:[1,0]
	v_mul_f32_e32 v145, v145, v100
	v_mul_f32_e32 v100, v126, v144
	v_mul_f32_e32 v126, v102, v100
	v_mul_f32_e32 v100, v127, v146
	v_mul_f32_e32 v121, v163, v121
	v_mul_f32_e32 v103, v103, v100
	global_store_dwordx4 v[188:189], v[152:155], off
	v_mul_f32_e32 v121, v147, v121
	v_cvt_pk_bf16_f32 v100, v111, v121
	v_cvt_pk_bf16_f32 v101, v123, v101
	v_cvt_pk_bf16_f32 v102, v125, v145
	v_cvt_pk_bf16_f32 v103, v126, v103
	global_store_dwordx4 v[160:161], v[100:103], off
	v_pk_mul_f32 v[84:85], v[84:85], v[156:157] op_sel_hi:[1,0]
	v_pk_mul_f32 v[118:119], v[118:119], v[156:157] op_sel_hi:[1,0]
	v_pk_mul_f32 v[102:103], v[142:143], v[156:157] op_sel_hi:[1,0]
	v_pk_mul_f32 v[126:127], v[140:141], v[156:157] op_sel_hi:[1,0]
	v_mul_f32_e32 v111, 0xbfb8aa3b, v102
	v_exp_f32_e32 v111, v111
	v_mul_f32_e32 v121, 0xbfb8aa3b, v103
	v_exp_f32_e32 v121, v121
	v_pk_mul_f32 v[92:93], v[92:93], v[156:157] op_sel_hi:[1,0]
	v_add_f32_e32 v111, 1.0, v111
	v_rcp_f32_e32 v111, v111
	v_add_f32_e32 v121, 1.0, v121
	v_rcp_f32_e32 v121, v121
	v_pk_mul_f32 v[86:87], v[86:87], v[156:157] op_sel_hi:[1,0]
	v_mul_f32_e32 v102, v102, v111
	v_mul_f32_e32 v111, 0xbfb8aa3b, v84
	v_mul_f32_e32 v102, v118, v102
	v_exp_f32_e32 v111, v111
	v_mul_f32_e32 v118, 0xbfb8aa3b, v85
	v_exp_f32_e32 v118, v118
	v_mul_f32_e32 v103, v103, v121
	v_add_f32_e32 v111, 1.0, v111
	v_mul_f32_e32 v103, v119, v103
	v_rcp_f32_e32 v111, v111
	v_add_f32_e32 v118, 1.0, v118
	v_mul_f32_e32 v119, 0xbfb8aa3b, v126
	v_rcp_f32_e32 v118, v118
	v_exp_f32_e32 v119, v119
	v_mul_f32_e32 v84, v84, v111
	v_mul_f32_e32 v92, v92, v84
	v_mul_f32_e32 v84, v85, v118
	v_add_f32_e32 v85, 1.0, v119
	v_rcp_f32_e32 v85, v85
	v_mul_f32_e32 v111, 0xbfb8aa3b, v127
	v_exp_f32_e32 v111, v111
	v_pk_mul_f32 v[116:117], v[116:117], v[156:157] op_sel_hi:[1,0]
	v_mul_f32_e32 v93, v93, v84
	v_mul_f32_e32 v84, v126, v85
	v_mul_f32_e32 v85, 0xbfb8aa3b, v86
	v_mul_f32_e32 v116, v116, v84
	v_add_f32_e32 v84, 1.0, v111
	v_exp_f32_e32 v85, v85
	v_mul_f32_e32 v111, 0xbfb8aa3b, v87
	v_exp_f32_e32 v111, v111
	v_rcp_f32_e32 v84, v84
	v_add_f32_e32 v85, 1.0, v85
	v_rcp_f32_e32 v85, v85
	v_add_f32_e32 v111, 1.0, v111
	v_rcp_f32_e32 v111, v111
	v_mul_f32_e32 v84, v127, v84
	v_pk_mul_f32 v[94:95], v[94:95], v[156:157] op_sel_hi:[1,0]
	v_mul_f32_e32 v117, v117, v84
	v_mul_f32_e32 v84, v86, v85
	v_mul_f32_e32 v94, v94, v84
	v_mul_f32_e32 v84, v87, v111
	v_mad_i64_i32 v[100:101], s[36:37], v157, s62, v[96:97]
	v_mul_f32_e32 v87, v95, v84
	v_lshl_add_u64 v[100:101], v[100:101], 0, v[108:109]
	v_cvt_pk_bf16_f32 v84, v102, v103
	v_cvt_pk_bf16_f32 v85, v92, v93
	v_cvt_pk_bf16_f32 v86, v116, v117
	v_cvt_pk_bf16_f32 v87, v94, v87
	global_store_dwordx4 v[100:101], v[84:87], off
	v_pk_mul_f32 v[76:77], v[76:77], v[124:125] op_sel_hi:[1,0]
	v_pk_mul_f32 v[94:95], v[106:107], v[124:125] op_sel_hi:[1,0]
	v_pk_mul_f32 v[86:87], v[114:115], v[124:125] op_sel_hi:[1,0]
	v_pk_mul_f32 v[92:93], v[112:113], v[124:125] op_sel_hi:[1,0]
	v_mul_f32_e32 v100, 0xbfb8aa3b, v86
	v_exp_f32_e32 v100, v100
	v_mul_f32_e32 v101, 0xbfb8aa3b, v87
	v_exp_f32_e32 v101, v101
	v_pk_mul_f32 v[80:81], v[80:81], v[124:125] op_sel_hi:[1,0]
	v_add_f32_e32 v100, 1.0, v100
	v_rcp_f32_e32 v100, v100
	v_add_f32_e32 v101, 1.0, v101
	v_rcp_f32_e32 v101, v101
	v_pk_mul_f32 v[78:79], v[78:79], v[124:125] op_sel_hi:[1,0]
	v_mul_f32_e32 v86, v86, v100
	v_mul_f32_e32 v86, v94, v86
	v_mul_f32_e32 v94, 0xbfb8aa3b, v76
	v_exp_f32_e32 v94, v94
	v_mul_f32_e32 v100, 0xbfb8aa3b, v77
	v_exp_f32_e32 v100, v100
	v_mul_f32_e32 v87, v87, v101
	v_add_f32_e32 v94, 1.0, v94
	v_mul_f32_e32 v87, v95, v87
	v_rcp_f32_e32 v94, v94
	v_add_f32_e32 v95, 1.0, v100
	v_mul_f32_e32 v100, 0xbfb8aa3b, v92
	v_rcp_f32_e32 v95, v95
	v_exp_f32_e32 v100, v100
	v_mul_f32_e32 v76, v76, v94
	v_mul_f32_e32 v80, v80, v76
	v_mul_f32_e32 v76, v77, v95
	v_add_f32_e32 v77, 1.0, v100
	v_rcp_f32_e32 v77, v77
	v_mul_f32_e32 v94, 0xbfb8aa3b, v93
	v_exp_f32_e32 v94, v94
	v_pk_mul_f32 v[98:99], v[98:99], v[124:125] op_sel_hi:[1,0]
	v_mul_f32_e32 v81, v81, v76
	v_mul_f32_e32 v76, v92, v77
	v_mul_f32_e32 v77, 0xbfb8aa3b, v78
	v_mul_f32_e32 v92, v98, v76
	v_add_f32_e32 v76, 1.0, v94
	v_exp_f32_e32 v77, v77
	v_mul_f32_e32 v94, 0xbfb8aa3b, v79
	v_rcp_f32_e32 v76, v76
	v_exp_f32_e32 v94, v94
	v_add_f32_e32 v77, 1.0, v77
	v_rcp_f32_e32 v77, v77
	v_mul_f32_e32 v76, v93, v76
	v_add_f32_e32 v93, 1.0, v94
	v_rcp_f32_e32 v93, v93
	v_pk_mul_f32 v[82:83], v[82:83], v[124:125] op_sel_hi:[1,0]
	v_mul_f32_e32 v94, v99, v76
	v_mul_f32_e32 v76, v78, v77
	v_mad_i64_i32 v[84:85], s[36:37], v159, s62, v[96:97]
	v_mul_f32_e32 v82, v82, v76
	v_mul_f32_e32 v76, v79, v93
	v_lshl_add_u64 v[84:85], v[84:85], 0, v[108:109]
	v_mul_f32_e32 v79, v83, v76
	v_cvt_pk_bf16_f32 v76, v86, v87
	v_cvt_pk_bf16_f32 v77, v80, v81
	v_cvt_pk_bf16_f32 v78, v92, v94
	v_pk_mul_f32 v[64:65], v[64:65], v[122:123] op_sel_hi:[1,0]
	v_cvt_pk_bf16_f32 v79, v82, v79
	global_store_dwordx4 v[84:85], v[76:79], off
	v_pk_mul_f32 v[66:67], v[66:67], v[122:123] op_sel_hi:[1,0]
	v_pk_mul_f32 v[70:71], v[70:71], v[122:123] op_sel_hi:[1,0]
	v_mul_f32_e32 v78, 0xbfb8aa3b, v64
	v_exp_f32_e32 v78, v78
	v_mul_f32_e32 v79, 0xbfb8aa3b, v65
	v_exp_f32_e32 v79, v79
	v_pk_mul_f32 v[60:61], v[60:61], v[122:123] op_sel_hi:[1,0]
	v_add_f32_e32 v78, 1.0, v78
	v_rcp_f32_e32 v78, v78
	v_add_f32_e32 v79, 1.0, v79
	v_rcp_f32_e32 v79, v79
	v_pk_mul_f32 v[62:63], v[62:63], v[122:123] op_sel_hi:[1,0]
	v_mul_f32_e32 v64, v64, v78
	v_mul_f32_e32 v64, v70, v64
	v_mul_f32_e32 v70, 0xbfb8aa3b, v66
	v_mul_f32_e32 v78, 0xbfb8aa3b, v67
	v_exp_f32_e32 v70, v70
	v_exp_f32_e32 v78, v78
	v_mul_f32_e32 v65, v65, v79
	v_mul_f32_e32 v65, v71, v65
	v_add_f32_e32 v70, 1.0, v70
	v_add_f32_e32 v71, 1.0, v78
	v_mul_f32_e32 v78, 0xbfb8aa3b, v60
	v_rcp_f32_e32 v70, v70
	v_exp_f32_e32 v78, v78
	v_rcp_f32_e32 v71, v71
	v_pk_mul_f32 v[68:69], v[68:69], v[122:123] op_sel_hi:[1,0]
	v_mul_f32_e32 v66, v66, v70
	v_add_f32_e32 v70, 1.0, v78
	v_mul_f32_e32 v67, v67, v71
	v_rcp_f32_e32 v70, v70
	v_mul_f32_e32 v71, 0xbfb8aa3b, v61
	v_exp_f32_e32 v71, v71
	v_pk_mul_f32 v[72:73], v[72:73], v[122:123] op_sel_hi:[1,0]
	v_mul_f32_e32 v60, v60, v70
	v_mul_f32_e32 v68, v68, v60
	v_add_f32_e32 v60, 1.0, v71
	v_mul_f32_e32 v70, 0xbfb8aa3b, v62
	v_rcp_f32_e32 v60, v60
	v_exp_f32_e32 v70, v70
	v_mul_f32_e32 v71, 0xbfb8aa3b, v63
	v_exp_f32_e32 v71, v71
	v_mul_f32_e32 v60, v61, v60
	v_add_f32_e32 v61, 1.0, v70
	v_rcp_f32_e32 v61, v61
	v_add_f32_e32 v70, 1.0, v71
	v_rcp_f32_e32 v70, v70
	v_mul_f32_e32 v69, v69, v60
	v_mul_f32_e32 v60, v62, v61
	v_mad_i64_i32 v[76:77], s[36:37], v179, s62, v[96:97]
	v_pk_mul_f32 v[74:75], v[74:75], v[122:123] op_sel_hi:[1,0]
	v_mul_f32_e32 v71, v72, v60
	v_mul_f32_e32 v60, v63, v70
	v_lshl_add_u64 v[76:77], v[76:77], 0, v[108:109]
	v_mul_f32_e32 v66, v74, v66
	v_mul_f32_e32 v67, v75, v67
	v_mul_f32_e32 v63, v73, v60
	v_cvt_pk_bf16_f32 v60, v64, v65
	v_cvt_pk_bf16_f32 v61, v66, v67
	v_cvt_pk_bf16_f32 v62, v68, v69
	v_pk_mul_f32 v[46:47], v[46:47], v[120:121] op_sel_hi:[1,0]
	v_cvt_pk_bf16_f32 v63, v71, v63
	global_store_dwordx4 v[76:77], v[60:63], off
	v_pk_mul_f32 v[52:53], v[52:53], v[120:121] op_sel_hi:[1,0]
	v_pk_mul_f32 v[54:55], v[54:55], v[120:121] op_sel_hi:[1,0]
	v_mul_f32_e32 v62, 0xbfb8aa3b, v46
	v_exp_f32_e32 v62, v62
	v_mul_f32_e32 v63, 0xbfb8aa3b, v47
	v_exp_f32_e32 v63, v63
	v_pk_mul_f32 v[44:45], v[44:45], v[120:121] op_sel_hi:[1,0]
	v_add_f32_e32 v62, 1.0, v62
	v_rcp_f32_e32 v62, v62
	v_add_f32_e32 v63, 1.0, v63
	v_rcp_f32_e32 v63, v63
	v_pk_mul_f32 v[48:49], v[48:49], v[120:121] op_sel_hi:[1,0]
	v_mul_f32_e32 v46, v46, v62
	v_mul_f32_e32 v46, v54, v46
	v_mul_f32_e32 v54, 0xbfb8aa3b, v52
	v_mul_f32_e32 v62, 0xbfb8aa3b, v53
	v_exp_f32_e32 v54, v54
	v_exp_f32_e32 v62, v62
	v_mul_f32_e32 v47, v47, v63
	v_mul_f32_e32 v47, v55, v47
	v_add_f32_e32 v54, 1.0, v54
	v_add_f32_e32 v55, 1.0, v62
	v_mul_f32_e32 v62, 0xbfb8aa3b, v44
	v_rcp_f32_e32 v54, v54
	v_exp_f32_e32 v62, v62
	v_rcp_f32_e32 v55, v55
	v_pk_mul_f32 v[50:51], v[50:51], v[120:121] op_sel_hi:[1,0]
	v_mul_f32_e32 v52, v52, v54
	v_add_f32_e32 v54, 1.0, v62
	v_mul_f32_e32 v53, v53, v55
	v_rcp_f32_e32 v54, v54
	v_mul_f32_e32 v55, 0xbfb8aa3b, v45
	v_exp_f32_e32 v55, v55
	v_pk_mul_f32 v[56:57], v[56:57], v[120:121] op_sel_hi:[1,0]
	v_mul_f32_e32 v44, v44, v54
	v_mul_f32_e32 v50, v50, v44
	v_add_f32_e32 v44, 1.0, v55
	v_mul_f32_e32 v54, 0xbfb8aa3b, v48
	v_rcp_f32_e32 v44, v44
	v_exp_f32_e32 v54, v54
	v_mul_f32_e32 v55, 0xbfb8aa3b, v49
	v_exp_f32_e32 v55, v55
	v_mul_f32_e32 v44, v45, v44
	v_add_f32_e32 v45, 1.0, v54
	v_rcp_f32_e32 v45, v45
	v_add_f32_e32 v54, 1.0, v55
	v_rcp_f32_e32 v54, v54
	v_mul_f32_e32 v51, v51, v44
	v_mul_f32_e32 v44, v48, v45
	v_mad_i64_i32 v[60:61], s[36:37], v149, s62, v[96:97]
	v_pk_mul_f32 v[58:59], v[58:59], v[120:121] op_sel_hi:[1,0]
	v_mul_f32_e32 v48, v56, v44
	v_mul_f32_e32 v44, v49, v54
	v_lshl_add_u64 v[60:61], v[60:61], 0, v[108:109]
	v_mul_f32_e32 v52, v58, v52
	v_mul_f32_e32 v53, v59, v53
	v_mul_f32_e32 v49, v57, v44
	v_cvt_pk_bf16_f32 v44, v46, v47
	v_cvt_pk_bf16_f32 v45, v52, v53
	v_cvt_pk_bf16_f32 v46, v50, v51
	v_pk_mul_f32 v[22:23], v[22:23], v[110:111] op_sel_hi:[1,0]
	v_cvt_pk_bf16_f32 v47, v48, v49
	global_store_dwordx4 v[60:61], v[44:47], off
	v_pk_mul_f32 v[10:11], v[10:11], v[104:105] op_sel_hi:[1,0]
	v_pk_mul_f32 v[30:31], v[30:31], v[110:111] op_sel_hi:[1,0]
	v_mul_f32_e32 v46, 0xbfb8aa3b, v22
	v_exp_f32_e32 v46, v46
	v_mul_f32_e32 v16, 0xbfb8aa3b, v10
	v_exp_f32_e32 v16, v16
	v_mul_f32_e32 v17, 0xbfb8aa3b, v11
	v_exp_f32_e32 v17, v17
	v_mul_f32_e32 v47, 0xbfb8aa3b, v23
	v_add_f32_e32 v46, 1.0, v46
	v_exp_f32_e32 v47, v47
	v_rcp_f32_e32 v46, v46
	v_add_f32_e32 v16, 1.0, v16
	v_rcp_f32_e32 v16, v16
	v_add_f32_e32 v17, 1.0, v17
	v_rcp_f32_e32 v17, v17
	v_pk_mul_f32 v[34:35], v[34:35], v[110:111] op_sel_hi:[1,0]
	v_add_f32_e32 v47, 1.0, v47
	v_mul_f32_e32 v22, v22, v46
	v_rcp_f32_e32 v47, v47
	v_mul_f32_e32 v22, v34, v22
	v_mul_f32_e32 v34, 0xbfb8aa3b, v30
	v_mul_f32_e32 v46, 0xbfb8aa3b, v31
	v_pk_mul_f32 v[14:15], v[14:15], v[104:105] op_sel_hi:[1,0]
	v_pk_mul_f32 v[4:5], v[4:5], v[104:105] op_sel_hi:[1,0]
	v_mul_f32_e32 v10, v10, v16
	v_exp_f32_e32 v34, v34
	v_exp_f32_e32 v46, v46
	v_mul_f32_e32 v4, v4, v10
	v_mul_f32_e32 v10, v11, v17
	v_mul_f32_e32 v11, 0xbfb8aa3b, v14
	v_exp_f32_e32 v11, v11
	v_mul_f32_e32 v16, 0xbfb8aa3b, v15
	v_exp_f32_e32 v16, v16
	v_pk_mul_f32 v[20:21], v[20:21], v[110:111] op_sel_hi:[1,0]
	v_mul_f32_e32 v23, v23, v47
	v_mul_f32_e32 v23, v35, v23
	v_add_f32_e32 v34, 1.0, v34
	v_add_f32_e32 v35, 1.0, v46
	v_mul_f32_e32 v46, 0xbfb8aa3b, v20
	v_rcp_f32_e32 v34, v34
	v_exp_f32_e32 v46, v46
	v_pk_mul_f32 v[8:9], v[8:9], v[104:105] op_sel_hi:[1,0]
	v_mul_f32_e32 v5, v5, v10
	v_add_f32_e32 v10, 1.0, v11
	v_rcp_f32_e32 v35, v35
	v_rcp_f32_e32 v10, v10
	v_add_f32_e32 v11, 1.0, v16
	v_mul_f32_e32 v16, 0xbfb8aa3b, v8
	v_rcp_f32_e32 v11, v11
	v_exp_f32_e32 v16, v16
	v_mul_f32_e32 v30, v30, v34
	v_add_f32_e32 v34, 1.0, v46
	v_mul_f32_e32 v31, v31, v35
	v_rcp_f32_e32 v34, v34
	v_mul_f32_e32 v35, 0xbfb8aa3b, v21
	v_pk_mul_f32 v[6:7], v[6:7], v[104:105] op_sel_hi:[1,0]
	v_mul_f32_e32 v10, v14, v10
	v_exp_f32_e32 v35, v35
	v_mul_f32_e32 v6, v6, v10
	v_mul_f32_e32 v10, v15, v11
	v_add_f32_e32 v11, 1.0, v16
	v_rcp_f32_e32 v11, v11
	v_mul_f32_e32 v14, 0xbfb8aa3b, v9
	v_exp_f32_e32 v14, v14
	v_pk_mul_f32 v[28:29], v[28:29], v[110:111] op_sel_hi:[1,0]
	v_pk_mul_f32 v[32:33], v[32:33], v[110:111] op_sel_hi:[1,0]
	v_mul_f32_e32 v20, v20, v34
	v_mul_f32_e32 v32, v32, v20
	v_add_f32_e32 v20, 1.0, v35
	v_mul_f32_e32 v34, 0xbfb8aa3b, v28
	v_rcp_f32_e32 v20, v20
	v_exp_f32_e32 v34, v34
	v_mul_f32_e32 v35, 0xbfb8aa3b, v29
	v_pk_mul_f32 v[12:13], v[12:13], v[104:105] op_sel_hi:[1,0]
	v_pk_mul_f32 v[0:1], v[0:1], v[104:105] op_sel_hi:[1,0]
	v_mul_f32_e32 v8, v8, v11
	v_exp_f32_e32 v35, v35
	v_mul_f32_e32 v7, v7, v10
	v_mul_f32_e32 v8, v0, v8
	v_add_f32_e32 v0, 1.0, v14
	v_mul_f32_e32 v10, 0xbfb8aa3b, v12
	v_rcp_f32_e32 v0, v0
	v_exp_f32_e32 v10, v10
	v_mul_f32_e32 v11, 0xbfb8aa3b, v13
	v_exp_f32_e32 v11, v11
	v_mul_f32_e32 v20, v21, v20
	v_add_f32_e32 v21, 1.0, v34
	v_rcp_f32_e32 v21, v21
	v_add_f32_e32 v34, 1.0, v35
	v_rcp_f32_e32 v34, v34
	v_mul_f32_e32 v0, v9, v0
	v_add_f32_e32 v9, 1.0, v10
	v_rcp_f32_e32 v9, v9
	v_add_f32_e32 v10, 1.0, v11
	v_rcp_f32_e32 v10, v10
	v_pk_mul_f32 v[36:37], v[36:37], v[110:111] op_sel_hi:[1,0]
	v_mul_f32_e32 v33, v33, v20
	v_mul_f32_e32 v20, v28, v21
	v_mad_i64_i32 v[44:45], s[36:37], v148, s62, v[96:97]
	v_pk_mul_f32 v[38:39], v[38:39], v[110:111] op_sel_hi:[1,0]
	v_mul_f32_e32 v28, v36, v20
	v_mul_f32_e32 v20, v29, v34
	v_lshl_add_u64 v[44:45], v[44:45], 0, v[108:109]
	v_mul_f32_e32 v30, v38, v30
	v_mul_f32_e32 v31, v39, v31
	v_mul_f32_e32 v29, v37, v20
	v_cvt_pk_bf16_f32 v20, v22, v23
	v_cvt_pk_bf16_f32 v21, v30, v31
	v_pk_mul_f32 v[2:3], v[2:3], v[104:105] op_sel_hi:[1,0]
	v_mul_f32_e32 v11, v1, v0
	v_mul_f32_e32 v0, v12, v9
	v_cvt_pk_bf16_f32 v22, v32, v33
	v_cvt_pk_bf16_f32 v23, v28, v29
	global_store_dwordx4 v[44:45], v[20:23], off
	v_mul_f32_e32 v9, v2, v0
	v_mul_f32_e32 v0, v13, v10
	v_mad_i64_i32 v[20:21], s[36:37], v105, s62, v[96:97]
	v_lshl_add_u64 v[20:21], v[20:21], 0, v[108:109]
	v_mul_f32_e32 v3, v3, v0
	v_cvt_pk_bf16_f32 v0, v4, v5
	v_cvt_pk_bf16_f32 v1, v6, v7
	v_cvt_pk_bf16_f32 v2, v8, v11
	v_cvt_pk_bf16_f32 v3, v9, v3
	global_store_dwordx4 v[20:21], v[0:3], off
